# v30 plus static s_setprio 1 for waves 4-7 during both PEER gather phases (SIMD partners de-phased)
# speedup vs baseline: 1.0049x; 1.0049x over previous
; DI int otid_w(int wave) { unsigned z = 0u; asm volatile("" : "+v"(z)); int t = wave * 64 + (int)__builtin_amdgcn_mbcnt_hi(~0u, __builtin_amdgcn_mbcnt_lo(~0u, z)); asm volatile("" : "+v"(t)); return t; }
; #define PEER_META(T, IA, IB, HA, HB) do { const int _t = (T) < TTOK ? (T) : wslot; \
;     IA = *(const u32x4*)(W_IDX(p) + (size_t)_t * 128 + r * 16); IB = *(const u32x4*)(W_IDX(p) + (size_t)_t * 128 + r * 16 + 8); \
;     const u16* _hp = W_H(p) + (size_t)_t * DM + x * 128 + 16 * c; HA = *(const u32x4*)(_hp); HB = *(const u32x4*)(_hp + 8); } while (0)
; #define PEER_GATHER(TAB, IA, IB, RR) do { _Pragma("unroll") for (int g = 0; g < 16; ++g) { \
;     const unsigned _w = (g < 8 ? IA : IB)[(g >> 1) & 3]; RR[g] = *(const u32x4*)((TAB) + row_off(_w, c16, (g & 1) != 0)); } } while (0)
; DI unsigned row_off(unsigned w, unsigned c16, bool hi) {
;   unsigned r; const unsigned m = 128u;
;   if (hi) asm("v_mad_u32_u16 %0, %1, %2, %3 op_sel:[1,0,0,0]" : "=v"(r) : "v"(w), "v"(m), "v"(c16));
;   else asm("v_mad_u32_u16 %0, %1, %2, %3" : "=v"(r) : "v"(w), "v"(m), "v"(c16));
;   return r;
; }
; DI void phase_peer_dots(const Params& p, int layer, int wave) {
;   const int tid = otid_w(wave), lane = tid & 63, wid = wave, c = lane & 7, r = lane >> 3;
;   const int x = blockIdx.x & 7, wslot = (blockIdx.x >> 3) * 8 + wid, nslot = (gridDim.x >> 3) * 8;
;   const unsigned char* ub = W_UB(p) + (size_t)x * (PEER_N * 128);
;   const unsigned c16 = (unsigned)c * 16u;
;   u16* pd = W_Y(p);
;   u32x4 iAa, iBa, iAb, iBb;
;   u32x4 hAa, hBa, hAb, hBb, rrA[16], rrB[16];
;   int xq[4];
;   float xscale;
;     ...
;   int t = wslot;
;   PEER_META(t, iAa, iBa, hAa, hBa);
;   PEER_META(t + nslot, iAb, iBb, hAb, hBb);
;   PEER_GATHER(ub, iAa, iBa, rrA);
.LBB0_125:
	s_and_b64 vcc, exec, s[0:1]
	s_cbranch_vccz .LBB0_133
	s_cmp_gt_i32 s96, 4
	s_mov_b64 s[56:57], -1
	s_cbranch_scc0 .LBB0_133
	s_waitcnt vmcnt(0)
	v_mov_b32_e32 v0, v177
	v_readlane_b32 s0, v253, 51
	v_mbcnt_lo_u32_b32 v0, -1, v0
	v_mbcnt_hi_u32_b32 v0, -1, v0
	v_add_u32_e32 v88, s64, v0
	v_readlane_b32 s1, v253, 52
	v_lshlrev_b32_e32 v0, 1, v88
	v_and_b32_e32 v0, 0x70, v0
	v_lshlrev_b32_e32 v176, 1, v0
	s_waitcnt lgkmcnt(0)
	s_nop 0
	global_load_dwordx4 v[4:7], v176, s[0:1]
	global_load_dwordx4 v[10:13], v176, s[0:1] offset:16
	v_readlane_b32 s0, v253, 56
	v_readlane_b32 s1, v253, 57
	v_and_b32_e32 v89, 7, v88
	s_andn2_b64 vcc, exec, s[0:1]
	v_lshlrev_b32_e32 v160, 4, v89
	s_waitcnt vmcnt(1)
	v_mad_u32_u16 v0, v4, v195, v160
	v_mad_u32_u16 v1, v4, v195, v160 op_sel:[1,0,0,0]
	v_mad_u32_u16 v2, v5, v195, v160
	v_mad_u32_u16 v3, v5, v195, v160 op_sel:[1,0,0,0]
	v_mad_u32_u16 v4, v6, v195, v160
	v_mad_u32_u16 v5, v6, v195, v160 op_sel:[1,0,0,0]
	v_mad_u32_u16 v6, v7, v195, v160
	v_mad_u32_u16 v7, v7, v195, v160 op_sel:[1,0,0,0]
	s_waitcnt vmcnt(0)
	v_mad_u32_u16 v8, v10, v195, v160
	v_mad_u32_u16 v9, v10, v195, v160 op_sel:[1,0,0,0]
	v_mad_u32_u16 v10, v11, v195, v160
	v_mad_u32_u16 v11, v11, v195, v160 op_sel:[1,0,0,0]
	v_mad_u32_u16 v16, v12, v195, v160
	v_mad_u32_u16 v12, v12, v195, v160 op_sel:[1,0,0,0]
	v_mad_u32_u16 v52, v13, v195, v160
	v_mad_u32_u16 v64, v13, v195, v160 op_sel:[1,0,0,0]
	s_cbranch_vccnz .LBB0_132
	global_load_dwordx4 v[12:15], v12, s[14:15]
	s_nop 0
	global_load_dwordx4 v[20:23], v16, s[14:15]
	global_load_dwordx4 v[24:27], v11, s[14:15]
	global_load_dwordx4 v[28:31], v10, s[14:15]
	global_load_dwordx4 v[32:35], v9, s[14:15]
	global_load_dwordx4 v[36:39], v8, s[14:15]
	global_load_dwordx4 v[40:43], v7, s[14:15]
	global_load_dwordx4 v[44:47], v6, s[14:15]
	global_load_dwordx4 v[48:51], v5, s[14:15]
	global_load_dwordx4 v[56:59], v4, s[14:15]
	global_load_dwordx4 v[60:63], v3, s[14:15]
	global_load_dwordx4 v[68:71], v2, s[14:15]
	global_load_dwordx4 v[72:75], v1, s[14:15]
	global_load_dwordx4 v[76:79], v0, s[14:15]
	v_readlane_b32 s0, v253, 60
	v_lshlrev_b32_e32 v90, 1, v160
	v_readlane_b32 s1, v253, 61
	s_nop 4
	global_load_dwordx4 v[0:3], v90, s[0:1] offset:16
	global_load_dwordx4 v[4:7], v90, s[0:1]
	v_readlane_b32 s0, v253, 62
	v_readlane_b32 s1, v253, 63
	s_nop 4
	global_load_dwordx4 v[80:83], v176, s[0:1] offset:16
	global_load_dwordx4 v[84:87], v176, s[0:1]
	v_readlane_b32 s0, v254, 2
	v_readlane_b32 s1, v254, 3
	s_nop 4
	global_load_dwordx4 v[8:11], v90, s[0:1] offset:16
	global_load_dwordx4 v[16:19], v90, s[0:1]
	s_nop 0
	global_load_dwordx4 v[52:55], v52, s[14:15]
	s_nop 0
	global_load_dwordx4 v[64:67], v64, s[14:15]
	v_readlane_b32 s0, v253, 54
	v_mov_b32_e32 v91, v177
	v_readlane_b32 s1, v253, 55
	v_readlane_b32 s12, v254, 4
	v_readlane_b32 s13, v254, 5
	v_lshl_add_u64 v[164:165], s[0:1], 0, v[90:91]
	v_and_b32_e32 v90, 2, v88
	v_cmp_eq_u32_e64 s[4:5], 0, v90
	v_and_b32_e32 v90, 1, v88
	v_lshl_add_u64 v[162:163], s[66:67], 0, v[176:177]
	v_cmp_eq_u32_e64 s[6:7], 0, v90
	v_lshl_add_u64 v[90:91], s[12:13], 0, v[176:177]
	v_lshlrev_b32_e32 v176, 1, v89
	v_lshlrev_b32_e32 v88, 2, v88
	s_movk_i32 s12, 0xe0
	v_lshl_add_u64 v[166:167], v[90:91], 0, v[176:177]
	v_and_or_b32 v176, v88, s12, v176
	v_readlane_b32 s12, v255, 14
	v_readlane_b32 s13, v255, 15
	v_cmp_lt_u32_e64 s[0:1], 3, v89
	s_nop 0
	v_lshl_add_u64 v[168:169], s[12:13], 0, v[176:177]
	s_mov_b32 s12, s38
	v_mbcnt_lo_u32_b32 v230, -1, 0
	v_mbcnt_hi_u32_b32 v230, -1, v230
	v_readlane_b32 s100, v253, 54
	v_readlane_b32 s101, v253, 55
	v_lshlrev_b32_e32 v228, 2, v230
	v_mov_b32_e32 v229, 0
	s_nop 1
	v_lshl_add_u64 v[226:227], s[100:101], 0, v[228:229]
	v_and_b32_e32 v231, 7, v230
	v_lshlrev_b32_e32 v231, 5, v231
	v_and_b32_e32 v230, 56, v230
	v_lshlrev_b32_e32 v230, 2, v230
	v_lshrrev_b32_e32 v228, 2, v160
	v_lshl_add_u64 v[224:225], v[162:163], 0, v[228:229]
	s_waitcnt vmcnt(0)
	v_readlane_b32 s100, v253, 50
	s_nop 3
	s_cmp_lt_u32 s100, 0x100
	s_cbranch_scc1 .Lpeer_prio_d
	s_setprio 1
.Lpeer_prio_d:
	s_branch .LBB0_130

; #define PEER_META(T, IA, IB, HA, HB) do { const int _t = (T) < TTOK ? (T) : wslot; \
;     IA = *(const u32x4*)(W_IDX(p) + (size_t)_t * 128 + r * 16); IB = *(const u32x4*)(W_IDX(p) + (size_t)_t * 128 + r * 16 + 8); \
;     const u16* _hp = W_H(p) + (size_t)_t * DM + x * 128 + 16 * c; HA = *(const u32x4*)(_hp); HB = *(const u32x4*)(_hp + 8); } while (0)
; #define PEER_GATHER(TAB, IA, IB, RR) do { _Pragma("unroll") for (int g = 0; g < 16; ++g) { \
;     const unsigned _w = (g < 8 ? IA : IB)[(g >> 1) & 3]; RR[g] = *(const u32x4*)((TAB) + row_off(_w, c16, (g & 1) != 0)); } } while (0)
; DI void phase_peer_dots(const Params& p, int layer, int wave) {
;     ...
;   for (; t < TTOK; t += 2 * nslot) {
;     DOTS_QUANT(hAa, hBa);
;     PEER_META(t + 2 * nslot, iAa, iBa, hAa, hBa);
;     PEER_GATHER(ub, iAb, iBb, rrB);
;     DOTS_COMPUTE(t, rrA);
;     DOTS_QUANT(hAb, hBb);
;     PEER_META(t + 3 * nslot, iAb, iBb, hAb, hBb);
;     PEER_GATHER(ub, iAa, iBa, rrA);
;     DOTS_COMPUTE(t + nslot, rrB);
;   }
;     ...
; }
.LBB0_132:
	s_setprio 0
	s_mov_b64 s[56:57], 0

; DI int otid_w(int wave) { unsigned z = 0u; asm volatile("" : "+v"(z)); int t = wave * 64 + (int)__builtin_amdgcn_mbcnt_hi(~0u, __builtin_amdgcn_mbcnt_lo(~0u, z)); asm volatile("" : "+v"(t)); return t; }
; #define PEER_GATHER(TAB, IA, IB, RR) do { _Pragma("unroll") for (int g = 0; g < 16; ++g) { \
;     const unsigned _w = (g < 8 ? IA : IB)[(g >> 1) & 3]; RR[g] = *(const u32x4*)((TAB) + row_off(_w, c16, (g & 1) != 0)); } } while (0)
; DI void phase_peer_v(const Params& p, int layer, int wave) {
;   const int tid = otid_w(wave), lane = tid & 63, wid = wave, c = lane & 7, r = lane >> 3;
;   const int x = blockIdx.x & 7, wslot = (blockIdx.x >> 3) * 8 + wid, nslot = (gridDim.x >> 3) * 8;
;   const unsigned char* vb = W_VB(p) + (size_t)x * (PEER_N * 128);
;   const unsigned c16 = (unsigned)c * 16u;
;   u16* y2 = W_Y(p);
;   const int ocol = x * 128 + 16 * c + 4 * ((lane >> 4) & 1) + 8 * (lane >> 5);
;   u32x4 iAa, iBa, iAb, iBb;
;   u32x4 wAa, wBa, wAb, wBb, wA, wB;
;   u32x2 hRa, hRb, hR;
;   u32x4 rrA[16], rrB[16];
;     ...
;   int t = wslot;
;   PEER_META_V(t, iAa, iBa, wAa, wBa, hRa);
;   PEER_META_V(t + nslot, iAb, iBb, wAb, wBb, hRb);
;   PEER_GATHER(vb, iAa, iBa, rrA);
.LBB0_184:
	s_and_b64 vcc, exec, s[78:79]
	s_cbranch_vccz .LBB0_195
	s_waitcnt vmcnt(0)
	v_mov_b32_e32 v0, v177
	v_readlane_b32 s0, v253, 51
	v_mbcnt_lo_u32_b32 v0, -1, v0
	v_mbcnt_hi_u32_b32 v0, -1, v0
	v_add_u32_e32 v0, s64, v0
	v_readlane_b32 s1, v253, 52
	v_lshlrev_b32_e32 v1, 1, v0
	v_and_b32_e32 v1, 0x70, v1
	v_lshlrev_b32_e32 v176, 1, v1
	s_waitcnt lgkmcnt(0)
	s_nop 0
	global_load_dwordx4 v[6:9], v176, s[0:1]
	global_load_dwordx4 v[12:15], v176, s[0:1] offset:16
	v_readlane_b32 s0, v253, 56
	v_readlane_b32 s1, v253, 57
	v_lshlrev_b32_e32 v1, 4, v0
	s_andn2_b64 vcc, exec, s[0:1]
	v_and_b32_e32 v205, 0x70, v1
	s_waitcnt vmcnt(1)
	v_mad_u32_u16 v2, v6, v195, v205
	v_mad_u32_u16 v3, v6, v195, v205 op_sel:[1,0,0,0]
	v_mad_u32_u16 v4, v7, v195, v205
	v_mad_u32_u16 v5, v7, v195, v205 op_sel:[1,0,0,0]
	v_mad_u32_u16 v6, v8, v195, v205
	v_mad_u32_u16 v7, v8, v195, v205 op_sel:[1,0,0,0]
	v_mad_u32_u16 v8, v9, v195, v205
	v_mad_u32_u16 v9, v9, v195, v205 op_sel:[1,0,0,0]
	s_waitcnt vmcnt(0)
	v_mad_u32_u16 v10, v12, v195, v205
	v_mad_u32_u16 v11, v12, v195, v205 op_sel:[1,0,0,0]
	v_mad_u32_u16 v16, v13, v195, v205
	v_mad_u32_u16 v17, v13, v195, v205 op_sel:[1,0,0,0]
	v_mad_u32_u16 v18, v14, v195, v205
	v_mad_u32_u16 v19, v14, v195, v205 op_sel:[1,0,0,0]
	v_mad_u32_u16 v12, v15, v195, v205
	v_mad_u32_u16 v1, v15, v195, v205 op_sel:[1,0,0,0]
	s_cbranch_vccnz .LBB0_194
	v_lshrrev_b32_e32 v13, 2, v0
	v_and_b32_e32 v38, 12, v13
	v_readlane_b32 s4, v253, 53
	v_readlane_b32 s0, v254, 28
	v_readlane_b32 s1, v254, 29
	v_or3_b32 v13, v38, s4, v205
	v_lshlrev_b32_e32 v36, 1, v13
	global_load_dwordx4 v[12:15], v12, s[80:81]
	s_nop 0
	global_load_dwordx4 v[20:23], v19, s[80:81]
	global_load_dwordx4 v[24:27], v18, s[80:81]
	global_load_dwordx4 v[28:31], v17, s[80:81]
	global_load_dwordx4 v[32:35], v16, s[80:81]
	global_load_dwordx4 v[40:43], v11, s[80:81]
	global_load_dwordx4 v[52:55], v10, s[80:81]
	global_load_dwordx4 v[60:63], v9, s[80:81]
	global_load_dwordx4 v[68:71], v8, s[80:81]
	global_load_dwordx4 v[80:83], v7, s[80:81]
	global_load_dwordx4 v[88:91], v6, s[80:81]
	global_load_dwordx4 v[96:99], v5, s[80:81]
	global_load_dwordx4 v[104:107], v4, s[80:81]
	global_load_dwordx4 v[112:115], v3, s[80:81]
	global_load_dwordx4 v[120:123], v2, s[80:81]
	v_lshl_add_u64 v[180:181], s[0:1], 0, v[176:177]
	v_readlane_b32 s0, v253, 58
	v_readlane_b32 s1, v253, 59
	v_and_b32_e32 v0, 8, v0
	v_lshl_add_u64 v[178:179], s[66:67], 0, v[176:177]
	v_mov_b32_e32 v37, v177
	v_lshl_add_u64 v[182:183], s[76:77], 0, v[36:37]
	v_lshl_add_u64 v[184:185], s[50:51], 0, v[36:37]
	global_load_dwordx2 v[186:187], v36, s[0:1]
	v_readlane_b32 s0, v254, 26
	v_readlane_b32 s1, v254, 27
	s_nop 4
	global_load_dwordx4 v[8:11], v176, s[0:1] offset:16
	global_load_dwordx4 v[72:75], v176, s[0:1]
	v_readlane_b32 s0, v253, 62
	v_readlane_b32 s1, v253, 63
	s_nop 4
	global_load_dwordx4 v[128:131], v176, s[0:1] offset:16
	global_load_dwordx4 v[140:143], v176, s[0:1]
	v_readlane_b32 s0, v254, 0
	v_readlane_b32 s1, v254, 1
	s_mov_b32 s8, s38
	s_nop 3
	global_load_dwordx2 v[160:161], v36, s[0:1]
	v_readlane_b32 s0, v254, 30
	v_readlane_b32 s1, v254, 31
	s_nop 4
	global_load_dwordx4 v[168:171], v176, s[0:1] offset:16
	global_load_dwordx4 v[172:175], v176, s[0:1]
	global_load_dwordx4 v[16:19], v1, s[80:81]
	v_cmp_eq_u32_e64 s[0:1], 0, v0
	v_add_u32_e32 v0, s4, v205
	v_readlane_b32 s4, v255, 20
	v_add_lshl_u32 v176, v0, v38, 1
	v_readlane_b32 s5, v255, 21
	s_nop 1
	v_lshl_add_u64 v[188:189], s[4:5], 0, v[176:177]
	v_lshrrev_b32_e32 v228, 2, v205
	v_mov_b32_e32 v229, 0
	v_lshl_add_u64 v[224:225], v[178:179], 0, v[228:229]
	v_lshl_add_u64 v[226:227], v[180:181], 0, v[228:229]
	v_mbcnt_lo_u32_b32 v230, -1, 0
	v_mbcnt_hi_u32_b32 v230, -1, v230
	v_and_b32_e32 v230, 56, v230
	v_lshlrev_b32_e32 v230, 2, v230
	s_waitcnt vmcnt(0)
	v_readlane_b32 s100, v253, 50
	s_nop 3
	s_cmp_lt_u32 s100, 0x100
	s_cbranch_scc1 .Lpeer_prio_v
	s_setprio 1
